# throttled row-phase loads: P7 row loop back to the baseline's load order (5 of the 8 O loads issued late, fewer bytes in flight), DPP sums kept
# speedup vs baseline: 1.0058x; 1.0037x over previous
; __device__ __forceinline__ void p7_rows(const Params& P, LAS unsigned char* lds, int G) {
;     ...
;         const int b = m >> 13; const f32x4* xr = (const f32x4*)(P.x + (size_t)m * DM) + lane; const u32x2* orow = (const u32x2*)(O + (size_t)m * DM) + lane;
;         f32x4 v[8], xv[8]; float ss = 0.f;
; #pragma unroll
;         for (int j = 0; j < 8; ++j) xv[j] = __builtin_nontemporal_load(xr + 64 * j);
; #pragma unroll
;         for (int j = 0; j < 8; ++j) { const u32x2 w = __builtin_nontemporal_load(orow + 64 * j); v[j][0] = __uint_as_float(w.x << 16); v[j][1] = __uint_as_float(w.x & 0xffff0000u); v[j][2] = __uint_as_float(w.y << 16); v[j][3] = __uint_as_float(w.y & 0xffff0000u);
;             ss += (v[j][0] * v[j][0] + v[j][1] * v[j][1]) + (v[j][2] * v[j][2] + v[j][3] * v[j][3]); }
;         const float rstd = rsqrtf(wave_sum(ss) * (1.0f / DM) + RMS_EPS);
.LBB0_803:
	v_add_co_u32_e32 v38, vcc, 0xf0800000, v36
	s_mov_b32 s33, 0xf0801000
	s_nop 0
	v_addc_co_u32_e32 v39, vcc, -1, v37, vcc
	v_add_co_u32_e32 v40, vcc, s33, v36
	global_load_dwordx4 v[28:31], v[34:35], off offset:-4096 nt
	global_load_dwordx4 v[24:27], v[34:35], off offset:-3072 nt
	global_load_dwordx4 v[20:23], v[34:35], off offset:-2048 nt
	global_load_dwordx4 v[16:19], v[34:35], off offset:-1024 nt
	global_load_dwordx4 v[12:15], v[34:35], off nt
	global_load_dwordx4 v[8:11], v[34:35], off offset:1024 nt
	global_load_dwordx4 v[4:7], v[34:35], off offset:2048 nt
	global_load_dwordx4 v[0:3], v[34:35], off offset:3072 nt
	v_addc_co_u32_e32 v41, vcc, -1, v37, vcc
	global_load_dwordx2 v[38:39], v[38:39], off nt
	s_mov_b32 s33, 0xec800000
	global_load_dwordx2 v[42:43], v[40:41], off offset:-3584 nt
	global_load_dwordx2 v[44:45], v[40:41], off offset:-3072 nt
	v_lshl_add_u64 v[34:35], v[34:35], 0, s[22:23]
	s_waitcnt vmcnt(2)
	v_and_b32_e32 v67, 0xffff0000, v38
	v_and_b32_e32 v69, 0xffff0000, v39
	v_lshlrev_b32_e32 v66, 16, v38
	s_waitcnt vmcnt(0)
	v_lshlrev_b32_e32 v58, 16, v44
	v_and_b32_e32 v59, 0xffff0000, v44
	v_lshlrev_b32_e32 v60, 16, v45
	v_and_b32_e32 v61, 0xffff0000, v45
	global_load_dwordx2 v[44:45], v[40:41], off offset:-2560 nt
	v_lshlrev_b32_e32 v68, 16, v39
	v_mul_f32_e32 v38, v69, v69
	v_and_b32_e32 v73, 0xffff0000, v43
	v_and_b32_e32 v72, 0xffff0000, v42
	v_pk_fma_f32 v[38:39], v[68:69], v[68:69], v[38:39] op_sel_hi:[1,1,0]
	v_lshlrev_b32_e32 v71, 16, v43
	v_lshlrev_b32_e32 v70, 16, v42
	v_pk_mul_f32 v[42:43], v[72:73], v[72:73]
	v_mov_b32_e32 v46, v38
	v_pk_fma_f32 v[42:43], v[70:71], v[70:71], v[42:43]
	s_waitcnt vmcnt(0)
	v_lshlrev_b32_e32 v55, 16, v44
	v_and_b32_e32 v51, 0xffff0000, v44
	v_mul_f32_e32 v44, v67, v67
	v_lshlrev_b32_e32 v48, 16, v45
	v_and_b32_e32 v49, 0xffff0000, v45
	v_pk_fma_f32 v[44:45], v[66:67], v[66:67], v[44:45] op_sel_hi:[1,1,0]
	v_mov_b32_e32 v47, v55
	v_mov_b32_e32 v54, v44
	v_mul_f32_e32 v50, v51, v51
	v_pk_add_f32 v[38:39], v[44:45], v[38:39]
	v_pk_mul_f32 v[44:45], v[54:55], v[46:47]
	v_pk_add_f32 v[42:43], v[42:43], v[42:43] op_sel:[0,1] op_sel_hi:[1,0]
	v_mov_b32_e32 v39, v45
	v_mov_b32_e32 v43, v50
	v_pk_add_f32 v[38:39], v[38:39], v[42:43]
	v_mul_f32_e32 v42, v59, v59
	v_mul_f32_e32 v44, v61, v61
	v_mul_f32_e32 v52, v48, v48
	v_mul_f32_e32 v53, v49, v49
	v_pk_fma_f32 v[42:43], v[58:59], v[58:59], v[42:43] op_sel_hi:[1,1,0]
	v_pk_fma_f32 v[44:45], v[60:61], v[60:61], v[44:45] op_sel_hi:[1,1,0]
	v_mov_b32_e32 v43, v52
	v_mov_b32_e32 v45, v53
	v_pk_add_f32 v[42:43], v[42:43], v[44:45]
	s_nop 0
	v_pk_add_f32 v[82:83], v[38:39], v[42:43]
	global_load_dwordx2 v[38:39], v[40:41], off offset:-2048 nt
	v_pk_add_f32 v[82:83], v[82:83], v[82:83] op_sel:[0,1] op_sel_hi:[1,0]
	s_waitcnt vmcnt(0)
	v_and_b32_e32 v65, 0xffff0000, v39
	v_and_b32_e32 v64, 0xffff0000, v38
	v_lshlrev_b32_e32 v63, 16, v39
	v_lshlrev_b32_e32 v62, 16, v38
	v_pk_mul_f32 v[38:39], v[64:65], v[64:65]
	v_mov_b32_e32 v42, v82
	v_pk_fma_f32 v[38:39], v[62:63], v[62:63], v[38:39]
	s_nop 0
	v_pk_add_f32 v[84:85], v[38:39], v[38:39] op_sel:[0,1] op_sel_hi:[1,0]
	global_load_dwordx2 v[38:39], v[40:41], off offset:-1536 nt
	v_mov_b32_e32 v88, v84
	v_pk_add_f32 v[82:83], v[82:83], v[84:85]
	s_waitcnt vmcnt(0)
	v_and_b32_e32 v57, 0xffff0000, v39
	v_and_b32_e32 v56, 0xffff0000, v38
	v_lshlrev_b32_e32 v53, 16, v39
	v_lshlrev_b32_e32 v52, 16, v38
	v_pk_mul_f32 v[38:39], v[56:57], v[56:57]
	s_nop 0
	v_pk_fma_f32 v[86:87], v[52:53], v[52:53], v[38:39]
	global_load_dwordx2 v[38:39], v[40:41], off offset:-1024 nt
	s_waitcnt vmcnt(0)
	v_lshlrev_b32_e32 v44, 16, v38
	v_and_b32_e32 v45, 0xffff0000, v38
	v_lshlrev_b32_e32 v46, 16, v39
	v_and_b32_e32 v47, 0xffff0000, v39
	global_load_dwordx2 v[38:39], v[40:41], off offset:-512 nt
	s_waitcnt vmcnt(0)
	v_lshlrev_b32_e32 v43, 16, v38
	v_mov_b32_e32 v89, v43
	v_and_b32_e32 v41, 0xffff0000, v38
	v_pk_mul_f32 v[84:85], v[42:43], v[88:89]
	v_mul_f32_e32 v40, v41, v41
	v_mov_b32_e32 v83, v85
	v_pk_add_f32 v[84:85], v[86:87], v[86:87] op_sel:[0,1] op_sel_hi:[1,0]
	v_lshlrev_b32_e32 v38, 16, v39
	v_mov_b32_e32 v85, v40
	v_mul_f32_e32 v40, v45, v45
	v_and_b32_e32 v39, 0xffff0000, v39
	v_pk_add_f32 v[82:83], v[82:83], v[84:85]
	v_pk_fma_f32 v[84:85], v[44:45], v[44:45], v[40:41] op_sel_hi:[1,1,0]
	v_mul_f32_e32 v40, v47, v47
	v_mul_f32_e32 v50, v38, v38
	v_mul_f32_e32 v54, v39, v39
	v_pk_fma_f32 v[86:87], v[46:47], v[46:47], v[40:41] op_sel_hi:[1,1,0]
	v_mov_b32_e32 v85, v50
	v_mov_b32_e32 v87, v54
	v_pk_add_f32 v[84:85], v[84:85], v[86:87]
	v_mov_b32_e32 v50, v55
	v_pk_add_f32 v[82:83], v[82:83], v[84:85]
	s_nop 0
	v_add_f32_e32 v40, v82, v83
	s_nop 1
	v_add_f32_dpp v40, v40, v40 quad_perm:[1,0,3,2] row_mask:0xf bank_mask:0xf
	s_nop 1
	v_add_f32_dpp v40, v40, v40 quad_perm:[2,3,0,1] row_mask:0xf bank_mask:0xf
	s_nop 1
	v_add_f32_dpp v40, v40, v40 row_half_mirror row_mask:0xf bank_mask:0xf
	s_nop 1
	v_add_f32_dpp v40, v40, v40 row_mirror row_mask:0xf bank_mask:0xf
	v_mov_b32_e32 v42, v40
	s_nop 1
	v_permlane16_swap_b32_e32 v42, v40
	v_add_f32_e32 v40, v40, v42
	v_mov_b32_e32 v42, v40
	s_nop 1
	v_permlane32_swap_b32_e32 v42, v40
	v_add_f32_e32 v40, v40, v42
	s_waitcnt lgkmcnt(0)
	v_fmamk_f32 v40, v40, 0x3a000000, v33
	v_cmp_gt_f32_e32 vcc, s3, v40
	v_mul_f32_e32 v42, 0x4b800000, v40
	s_nop 0
	v_cndmask_b32_e32 v40, v40, v42, vcc
	v_rsq_f32_e32 v40, v40
	s_nop 0
	v_mul_f32_e32 v42, 0x45800000, v40
	v_cndmask_b32_e32 v42, v40, v42, vcc
	v_and_b32_e32 v40, 0xffffe000, v32
	v_add_u32_e32 v54, v80, v40
	ds_read_b128 v[82:85], v54
	v_pk_mul_f32 v[66:67], v[42:43], v[66:67] op_sel_hi:[0,1]
	v_pk_mul_f32 v[68:69], v[42:43], v[68:69] op_sel_hi:[0,1]
	v_pk_mul_f32 v[50:51], v[50:51], v[42:43] op_sel_hi:[1,0]
	v_pk_mul_f32 v[48:49], v[48:49], v[42:43] op_sel_hi:[1,0]
	s_waitcnt lgkmcnt(0)
; #define LAS __attribute__((address_space(3)))
; __device__ __forceinline__ unsigned pk2(float lo, float hi) { return pg8::cvtpk(lo, hi); }
; __device__ __forceinline__ void p7_rows(const Params& P, LAS unsigned char* lds, int G) {
;     ...
;         for (int j = 0; j < 8; ++j) { const f32x4 a = *(const LAS f32x4*)(TA + b * DM + 256 * j + 4 * lane); const f32x4 x1 = xv[j] + v[j] * rstd * a; v[j] = x1; { u32x2 w; w.x = pk2(x1[0], x1[1]); w.y = pk2(x1[2], x1[3]); __builtin_nontemporal_store(w, x1r + 64 * j); }
;             s2 += (x1[0] * x1[0] + x1[1] * x1[1]) + (x1[2] * x1[2] + x1[3] * x1[3]); }
	v_pk_fma_f32 v[84:85], v[84:85], v[68:69], v[30:31]
	v_pk_fma_f32 v[82:83], v[82:83], v[66:67], v[28:29]
	v_cvt_pk_bf16_f32 v29, v84, v85
	v_cvt_pk_bf16_f32 v28, v82, v83
	global_store_dwordx2 v[36:37], v[28:29], off nt
	ds_read_b128 v[28:31], v54 offset:1024
	v_mov_b32_e32 v66, v70
	v_mov_b32_e32 v67, v72
	v_mov_b32_e32 v72, v71
	v_pk_mul_f32 v[66:67], v[42:43], v[66:67] op_sel_hi:[0,1]
	v_pk_mul_f32 v[68:69], v[42:43], v[72:73] op_sel_hi:[0,1]
	s_waitcnt lgkmcnt(0)
	v_pk_fma_f32 v[26:27], v[30:31], v[68:69], v[26:27]
	v_pk_fma_f32 v[28:29], v[28:29], v[66:67], v[24:25]
	v_cvt_pk_bf16_f32 v25, v26, v27
	v_cvt_pk_bf16_f32 v24, v28, v29
	v_mov_b32_e32 v30, v83
	v_mov_b32_e32 v31, v29
	global_store_dwordx2 v[36:37], v[24:25], off offset:512 nt
	v_mov_b32_e32 v24, v82
	v_mov_b32_e32 v25, v28
	v_pk_mul_f32 v[30:31], v[30:31], v[30:31]
	v_mov_b32_e32 v66, v85
	v_mov_b32_e32 v67, v27
	v_pk_fma_f32 v[24:25], v[24:25], v[24:25], v[30:31]
	v_mov_b32_e32 v30, v84
	v_mov_b32_e32 v31, v26
	v_pk_mul_f32 v[66:67], v[66:67], v[66:67]
	v_pk_mul_f32 v[44:45], v[42:43], v[44:45] op_sel_hi:[0,1]
	v_pk_fma_f32 v[30:31], v[30:31], v[30:31], v[66:67]
	ds_read_b128 v[66:69], v54 offset:2048
	v_pk_add_f32 v[24:25], v[24:25], v[30:31]
	v_pk_mul_f32 v[30:31], v[42:43], v[58:59] op_sel_hi:[0,1]
	v_pk_mul_f32 v[58:59], v[42:43], v[60:61] op_sel_hi:[0,1]
	v_pk_add_f32 v[24:25], v[24:25], v[24:25] op_sel_hi:[0,1]
	s_waitcnt lgkmcnt(0)
	v_pk_fma_f32 v[22:23], v[68:69], v[58:59], v[22:23]
	v_pk_fma_f32 v[20:21], v[66:67], v[30:31], v[20:21]
	v_cvt_pk_bf16_f32 v31, v22, v23
	v_cvt_pk_bf16_f32 v30, v20, v21
	global_store_dwordx2 v[36:37], v[30:31], off offset:1024 nt
	v_pk_mul_f32 v[30:31], v[22:23], v[22:23]
	v_pk_mul_f32 v[58:59], v[20:21], v[20:21]
	v_mov_b32_e32 v66, v62
	v_pk_mov_b32 v[60:61], v[58:59], v[30:31] op_sel:[1,0]
	v_mov_b32_e32 v59, v31
	v_pk_add_f32 v[30:31], v[60:61], v[58:59]
	ds_read_b128 v[58:61], v54 offset:3072
	v_mov_b32_e32 v67, v64
	v_mov_b32_e32 v64, v63
	v_pk_mul_f32 v[66:67], v[42:43], v[66:67] op_sel_hi:[0,1]
	v_pk_mul_f32 v[62:63], v[42:43], v[64:65] op_sel_hi:[0,1]
	s_waitcnt lgkmcnt(0)
	v_pk_fma_f32 v[18:19], v[60:61], v[48:49], v[18:19]
	v_pk_fma_f32 v[16:17], v[58:59], v[50:51], v[16:17]
	v_cvt_pk_bf16_f32 v49, v18, v19
	v_cvt_pk_bf16_f32 v48, v16, v17
	global_store_dwordx2 v[36:37], v[48:49], off offset:1536 nt
	ds_read_b128 v[48:51], v54 offset:4096
	v_mul_f32_e32 v24, v16, v16
	v_pk_fma_f32 v[58:59], v[16:17], v[16:17], v[24:25] op_sel_hi:[1,1,0]
	v_mul_f32_e32 v24, v18, v18
	v_pk_add_f32 v[30:31], v[30:31], v[30:31] op_sel_hi:[0,1]
	v_pk_fma_f32 v[60:61], v[18:19], v[18:19], v[24:25] op_sel_hi:[1,1,0]
	s_waitcnt lgkmcnt(0)
	v_pk_fma_f32 v[14:15], v[50:51], v[62:63], v[14:15]
	v_pk_fma_f32 v[12:13], v[48:49], v[66:67], v[12:13]
	v_cvt_pk_bf16_f32 v49, v14, v15
	v_cvt_pk_bf16_f32 v48, v12, v13
	v_mul_f32_e32 v58, v12, v12
	v_mul_f32_e32 v60, v13, v13
	v_mul_f32_e32 v30, v14, v14
	v_mul_f32_e32 v24, v15, v15
	global_store_dwordx2 v[36:37], v[48:49], off offset:2048 nt
	v_pk_add_f32 v[48:49], v[58:59], v[60:61]
	v_pk_add_f32 v[24:25], v[30:31], v[24:25]
	v_mov_b32_e32 v30, v52
	v_pk_add_f32 v[24:25], v[48:49], v[24:25]
	ds_read_b128 v[48:51], v54 offset:5120
	v_mov_b32_e32 v31, v56
	v_mov_b32_e32 v56, v53
	v_pk_mul_f32 v[30:31], v[42:43], v[30:31] op_sel_hi:[0,1]
	v_pk_mul_f32 v[52:53], v[42:43], v[56:57] op_sel_hi:[0,1]
	s_waitcnt lgkmcnt(0)
	v_pk_fma_f32 v[10:11], v[50:51], v[52:53], v[10:11]
	v_pk_fma_f32 v[8:9], v[48:49], v[30:31], v[8:9]
	v_cvt_pk_bf16_f32 v31, v10, v11
	v_cvt_pk_bf16_f32 v30, v8, v9
	global_store_dwordx2 v[36:37], v[30:31], off offset:2560 nt
	v_pk_mul_f32 v[30:31], v[10:11], v[10:11]
	v_pk_mul_f32 v[48:49], v[8:9], v[8:9]
	v_pk_mul_f32 v[46:47], v[42:43], v[46:47] op_sel_hi:[0,1]
	v_pk_mov_b32 v[50:51], v[48:49], v[30:31] op_sel:[1,0]
	v_mov_b32_e32 v49, v31
	v_pk_add_f32 v[30:31], v[50:51], v[48:49]
	ds_read_b128 v[48:51], v54 offset:6144
	v_pk_add_f32 v[24:25], v[24:25], v[24:25] op_sel_hi:[0,1]
	v_mov_b32_e32 v40, v43
	v_pk_mul_f32 v[40:41], v[40:41], v[42:43] op_sel_hi:[1,0]
	v_pk_mul_f32 v[38:39], v[38:39], v[42:43] op_sel_hi:[1,0]
	s_waitcnt lgkmcnt(0)
	v_pk_fma_f32 v[6:7], v[50:51], v[46:47], v[6:7]
	v_pk_fma_f32 v[4:5], v[48:49], v[44:45], v[4:5]
	v_cvt_pk_bf16_f32 v45, v6, v7
	v_cvt_pk_bf16_f32 v44, v4, v5
	global_store_dwordx2 v[36:37], v[44:45], off offset:3072 nt
	ds_read_b128 v[44:47], v54 offset:7168
	v_mul_f32_e32 v24, v4, v4
	v_pk_fma_f32 v[48:49], v[4:5], v[4:5], v[24:25] op_sel_hi:[1,1,0]
	v_mul_f32_e32 v24, v6, v6
	v_pk_add_f32 v[30:31], v[30:31], v[30:31] op_sel_hi:[0,1]
	v_pk_fma_f32 v[50:51], v[6:7], v[6:7], v[24:25] op_sel_hi:[1,1,0]
	s_waitcnt lgkmcnt(0)
; #define LAS __attribute__((address_space(3)))
; __device__ __forceinline__ unsigned pk2(float lo, float hi) { return pg8::cvtpk(lo, hi); }
; __device__ __forceinline__ void p7_rows(const Params& P, LAS unsigned char* lds, int G) {
;     ...
;         for (int j = 0; j < 8; ++j) { const f32x4 a = *(const LAS f32x4*)(TA + b * DM + 256 * j + 4 * lane); const f32x4 x1 = xv[j] + v[j] * rstd * a; v[j] = x1; { u32x2 w; w.x = pk2(x1[0], x1[1]); w.y = pk2(x1[2], x1[3]); __builtin_nontemporal_store(w, x1r + 64 * j); }
;             s2 += (x1[0] * x1[0] + x1[1] * x1[1]) + (x1[2] * x1[2] + x1[3] * x1[3]); }
;         const float rstd2 = rsqrtf(wave_sum(s2) * (1.0f / DM) + RMS_EPS);
;         u32x2* o = (u32x2*)(XN + (size_t)m * DM) + lane;
; #pragma unroll
;         for (int j = 0; j < 8; ++j) { const f32x4 a = *(const LAS f32x4*)(TB + b * DM + 256 * j + 4 * lane), c = *(const LAS f32x4*)(TC + b * DM + 256 * j + 4 * lane);
;             const f32x4 h = v[j] * rstd2 * a + c; u32x2 w; w.x = pk2(h[0], h[1]); w.y = pk2(h[2], h[3]); o[64 * j] = w; }
	v_pk_fma_f32 v[2:3], v[46:47], v[38:39], v[2:3]
	v_pk_fma_f32 v[0:1], v[44:45], v[40:41], v[0:1]
	v_cvt_pk_bf16_f32 v39, v2, v3
	v_cvt_pk_bf16_f32 v38, v0, v1
	v_mul_f32_e32 v48, v0, v0
	v_mul_f32_e32 v50, v1, v1
	v_mul_f32_e32 v30, v2, v2
	v_mul_f32_e32 v24, v3, v3
	global_store_dwordx2 v[36:37], v[38:39], off offset:3584 nt
	v_pk_add_f32 v[38:39], v[48:49], v[50:51]
	v_pk_add_f32 v[24:25], v[30:31], v[24:25]
	v_add_u32_e32 v32, s42, v32
	v_pk_add_f32 v[24:25], v[38:39], v[24:25]
	ds_read_b128 v[38:41], v54 offset:16384
	ds_read_b128 v[42:45], v54 offset:32768
	v_add_f32_e32 v24, v24, v25
	s_nop 1
	v_add_f32_dpp v24, v24, v24 quad_perm:[1,0,3,2] row_mask:0xf bank_mask:0xf
	s_nop 1
	v_add_f32_dpp v24, v24, v24 quad_perm:[2,3,0,1] row_mask:0xf bank_mask:0xf
	s_nop 1
	v_add_f32_dpp v24, v24, v24 row_half_mirror row_mask:0xf bank_mask:0xf
	s_nop 1
	v_add_f32_dpp v24, v24, v24 row_mirror row_mask:0xf bank_mask:0xf
	v_mov_b32_e32 v25, v24
	s_nop 1
	v_permlane16_swap_b32_e32 v25, v24
	v_add_f32_e32 v24, v24, v25
	v_mov_b32_e32 v25, v24
	s_nop 1
	v_permlane32_swap_b32_e32 v25, v24
	v_add_f32_e32 v24, v24, v25
	s_waitcnt lgkmcnt(0)
	v_fmamk_f32 v24, v24, 0x3a000000, v33
	v_cmp_gt_f32_e32 vcc, s3, v24
	v_mul_f32_e32 v25, 0x4b800000, v24
	s_nop 0
	v_cndmask_b32_e32 v24, v24, v25, vcc
	v_rsq_f32_e32 v24, v24
	s_nop 0
	v_mul_f32_e32 v25, 0x45800000, v24
	v_cndmask_b32_e32 v24, v24, v25, vcc
	v_pk_mul_f32 v[30:31], v[82:83], v[24:25] op_sel_hi:[1,0]
	v_pk_mul_f32 v[46:47], v[84:85], v[24:25] op_sel_hi:[1,0]
	v_pk_fma_f32 v[30:31], v[38:39], v[30:31], v[42:43]
	v_pk_fma_f32 v[40:41], v[40:41], v[46:47], v[44:45]
	v_add_co_u32_e32 v38, vcc, s33, v36
	v_cvt_pk_bf16_f32 v30, v30, v31
	v_cvt_pk_bf16_f32 v31, v40, v41
	v_addc_co_u32_e32 v39, vcc, -1, v37, vcc
	global_store_dwordx2 v[38:39], v[30:31], off
	ds_read_b128 v[38:41], v54 offset:17408
	ds_read_b128 v[42:45], v54 offset:33792
	v_pk_mul_f32 v[28:29], v[28:29], v[24:25] op_sel_hi:[1,0]
	v_pk_mul_f32 v[26:27], v[26:27], v[24:25] op_sel_hi:[1,0]
	s_mov_b32 s33, 0xec801000
	v_pk_mul_f32 v[20:21], v[20:21], v[24:25] op_sel_hi:[1,0]
	s_waitcnt lgkmcnt(0)
	v_pk_fma_f32 v[30:31], v[40:41], v[26:27], v[44:45]
	v_pk_fma_f32 v[26:27], v[38:39], v[28:29], v[42:43]
	v_pk_mul_f32 v[22:23], v[22:23], v[24:25] op_sel_hi:[1,0]
	v_cvt_pk_bf16_f32 v26, v26, v27
	v_cvt_pk_bf16_f32 v27, v30, v31
	v_add_co_u32_e32 v30, vcc, s33, v36
	v_pk_mul_f32 v[16:17], v[16:17], v[24:25] op_sel_hi:[1,0]
	s_nop 0
	v_addc_co_u32_e32 v31, vcc, -1, v37, vcc
	global_store_dwordx2 v[30:31], v[26:27], off offset:-3584
	ds_read_b128 v[26:29], v54 offset:18432
	ds_read_b128 v[38:41], v54 offset:34816
	v_pk_mul_f32 v[18:19], v[18:19], v[24:25] op_sel_hi:[1,0]
	v_pk_mul_f32 v[12:13], v[12:13], v[24:25] op_sel_hi:[1,0]
	v_pk_mul_f32 v[14:15], v[14:15], v[24:25] op_sel_hi:[1,0]
	v_pk_mul_f32 v[8:9], v[8:9], v[24:25] op_sel_hi:[1,0]
	s_waitcnt lgkmcnt(0)
	v_pk_fma_f32 v[22:23], v[28:29], v[22:23], v[40:41]
	v_pk_fma_f32 v[20:21], v[26:27], v[20:21], v[38:39]
	v_pk_mul_f32 v[10:11], v[10:11], v[24:25] op_sel_hi:[1,0]
	v_cvt_pk_bf16_f32 v20, v20, v21
	v_cvt_pk_bf16_f32 v21, v22, v23
	global_store_dwordx2 v[30:31], v[20:21], off offset:-3072
	ds_read_b128 v[20:23], v54 offset:19456
	ds_read_b128 v[26:29], v54 offset:35840
	v_pk_mul_f32 v[4:5], v[4:5], v[24:25] op_sel_hi:[1,0]
	v_pk_mul_f32 v[6:7], v[6:7], v[24:25] op_sel_hi:[1,0]
	v_pk_mul_f32 v[0:1], v[0:1], v[24:25] op_sel_hi:[1,0]
	v_pk_mul_f32 v[2:3], v[2:3], v[24:25] op_sel_hi:[1,0]
	s_waitcnt lgkmcnt(0)
	v_pk_fma_f32 v[18:19], v[22:23], v[18:19], v[28:29]
	v_pk_fma_f32 v[16:17], v[20:21], v[16:17], v[26:27]
	s_and_b32 s33, s2, 7
	s_lshl_b32 s33, s33, 11
	s_addk_i32 s33, 0x7ff
	s_cmpk_eq_u32 s92, 0x100
	s_cselect_b32 s33, s33, 0x3fff
	v_cvt_pk_bf16_f32 v16, v16, v17
	v_cvt_pk_bf16_f32 v17, v18, v19
	global_store_dwordx2 v[30:31], v[16:17], off offset:-2560
	ds_read_b128 v[16:19], v54 offset:20480
	ds_read_b128 v[20:23], v54 offset:36864
	v_cmp_lt_i32_e32 vcc, s33, v32
	v_lshl_add_u64 v[36:37], v[36:37], 0, s[26:27]
	s_or_b64 s[30:31], vcc, s[30:31]
	s_waitcnt lgkmcnt(0)
	v_pk_fma_f32 v[14:15], v[18:19], v[14:15], v[22:23]
	v_pk_fma_f32 v[12:13], v[16:17], v[12:13], v[20:21]
	s_nop 0
	v_cvt_pk_bf16_f32 v12, v12, v13
	v_cvt_pk_bf16_f32 v13, v14, v15
	global_store_dwordx2 v[30:31], v[12:13], off offset:-2048
	ds_read_b128 v[12:15], v54 offset:21504
	ds_read_b128 v[16:19], v54 offset:37888
	s_waitcnt lgkmcnt(0)
	v_pk_fma_f32 v[10:11], v[14:15], v[10:11], v[18:19]
	v_pk_fma_f32 v[8:9], v[12:13], v[8:9], v[16:17]
	s_nop 0
	v_cvt_pk_bf16_f32 v8, v8, v9
	v_cvt_pk_bf16_f32 v9, v10, v11
	global_store_dwordx2 v[30:31], v[8:9], off offset:-1536
	ds_read_b128 v[8:11], v54 offset:22528
	ds_read_b128 v[12:15], v54 offset:38912
	s_waitcnt lgkmcnt(0)
	v_pk_fma_f32 v[6:7], v[10:11], v[6:7], v[14:15]
	v_pk_fma_f32 v[4:5], v[8:9], v[4:5], v[12:13]
	s_nop 0
	v_cvt_pk_bf16_f32 v4, v4, v5
	v_cvt_pk_bf16_f32 v5, v6, v7
	global_store_dwordx2 v[30:31], v[4:5], off offset:-1024
	ds_read_b128 v[4:7], v54 offset:23552
	ds_read_b128 v[8:11], v54 offset:39936
	s_waitcnt lgkmcnt(0)
	v_pk_fma_f32 v[2:3], v[6:7], v[2:3], v[10:11]
	v_pk_fma_f32 v[0:1], v[4:5], v[0:1], v[8:9]
	s_nop 0
	v_cvt_pk_bf16_f32 v0, v0, v1
	v_cvt_pk_bf16_f32 v1, v2, v3
	global_store_dwordx2 v[30:31], v[0:1], off offset:-512
	s_andn2_b64 exec, exec, s[30:31]
	s_cbranch_execnz .LBB0_803
